# pipelined GEMM K-loops: next-stage LDS-DMA pieces issued three per MFMA group at the front of the stage
# baseline (speedup 1.0000x reference)
; template <int EPI, int MI>
; DI void gemm_tile(const GemmDesc& g, int tm, int tn, char* smem) {
;     ...
;   const int rowA = wm * (32 * MI) + r, rowB = wn * 64 + r;
;   const int hk = hh ^ ((r & 7) ^ ((r >> 3) & 3));
;     ...
;   G_GLDS(0, 0);
;   asm volatile("s_waitcnt vmcnt(0)" ::: "memory");
;   __syncthreads();
;   for (int kt = 0; kt < nk; kt += 2) {
;     if (kt + 1 < nk) G_GLDS(kt + 1, 1);
;     G_COMPUTE(0);
;     asm volatile("s_waitcnt vmcnt(0)" ::: "memory");
;     __syncthreads();
;     if (kt + 1 < nk) {
;       if (kt + 2 < nk) G_GLDS(kt + 2, 0);
;       G_COMPUTE(1);
;       asm volatile("s_waitcnt vmcnt(0)" ::: "memory");
;       __syncthreads();
;     }
;   }
.Lga_loop:
	ds_read_b128 v[232:235], v162 offset:8192
	s_waitcnt lgkmcnt(2)
	v_mfma_f32_32x32x16_bf16 v[80:95], v[224:227], v[236:239], v[80:95]
	v_mfma_f32_32x32x16_bf16 v[64:79], v[224:227], v[240:243], v[64:79]
	s_add_u32 m0, s100, 0x6000
	v_lshl_add_u64 v[106:107], v[174:175], 0, s[96:97]
	global_load_lds_dwordx4 v[106:107], off
	s_add_u32 m0, s100, 0x7000
	v_lshl_add_u64 v[106:107], v[174:175], 0, s[50:51]
	global_load_lds_dwordx4 v[106:107], off
	s_add_u32 m0, s100, 0x8000
	v_lshl_add_u64 v[106:107], v[174:175], 0, s[24:25]
	global_load_lds_dwordx4 v[106:107], off
	ds_read_b128 v[244:247], v167 offset:49152
	ds_read_b128 v[248:251], v167 offset:53248
	ds_read_b128 v[224:227], v163
	s_waitcnt lgkmcnt(4)
	v_mfma_f32_32x32x16_bf16 v[48:63], v[228:231], v[236:239], v[48:63]
	v_mfma_f32_32x32x16_bf16 v[32:47], v[228:231], v[240:243], v[32:47]
	s_add_u32 m0, s100, 0x9000
	v_lshl_add_u64 v[106:107], v[174:175], 0, s[26:27]
	global_load_lds_dwordx4 v[106:107], off
	s_add_u32 m0, s100, 0xa000
	v_lshl_add_u64 v[106:107], v[174:175], 0, s[28:29]
	global_load_lds_dwordx4 v[106:107], off
	s_add_u32 m0, s100, 0xb000
	v_lshl_add_u64 v[106:107], v[174:175], 0, s[30:31]
	global_load_lds_dwordx4 v[106:107], off
	v_lshl_add_u64 v[174:175], v[174:175], 0, s[18:19]
	ds_read_b128 v[228:231], v163 offset:4096
	s_waitcnt lgkmcnt(4)
	v_mfma_f32_32x32x16_bf16 v[16:31], v[232:235], v[236:239], v[16:31]
	v_mfma_f32_32x32x16_bf16 v[0:15], v[232:235], v[240:243], v[0:15]
	s_add_u32 m0, s100, 0x10000
	v_lshl_add_u64 v[106:107], v[176:177], 0, s[18:19]
	global_load_lds_dwordx4 v[106:107], off
	s_add_u32 m0, s100, 0x11000
	v_lshl_add_u64 v[106:107], v[176:177], 0, s[42:43]
	global_load_lds_dwordx4 v[106:107], off
	s_mov_b64 s[16:17], 0x20080
	s_add_u32 m0, s100, 0x12000
	v_lshl_add_u64 v[106:107], v[176:177], 0, s[16:17]
	global_load_lds_dwordx4 v[106:107], off
	ds_read_b128 v[232:235], v163 offset:8192
	s_waitcnt lgkmcnt(2)
	v_mfma_f32_32x32x16_bf16 v[80:95], v[224:227], v[244:247], v[80:95]
	v_mfma_f32_32x32x16_bf16 v[64:79], v[224:227], v[248:251], v[64:79]
	s_mov_b64 s[16:17], 0x30080
	s_add_u32 m0, s100, 0x13000
	v_lshl_add_u64 v[106:107], v[176:177], 0, s[16:17]
	global_load_lds_dwordx4 v[106:107], off
	v_lshl_add_u64 v[176:177], v[176:177], 0, s[18:19]
	ds_read_b128 v[236:239], v168 offset:49152
	ds_read_b128 v[240:243], v168 offset:53248
	ds_read_b128 v[224:227], v164
	s_waitcnt lgkmcnt(4)
	v_mfma_f32_32x32x16_bf16 v[48:63], v[228:231], v[244:247], v[48:63]
	v_mfma_f32_32x32x16_bf16 v[32:47], v[228:231], v[248:251], v[32:47]
	ds_read_b128 v[228:231], v164 offset:4096
	s_waitcnt lgkmcnt(4)
	v_mfma_f32_32x32x16_bf16 v[16:31], v[232:235], v[244:247], v[16:31]
	v_mfma_f32_32x32x16_bf16 v[0:15], v[232:235], v[248:251], v[0:15]
	ds_read_b128 v[232:235], v164 offset:8192
	s_waitcnt lgkmcnt(2)
	v_mfma_f32_32x32x16_bf16 v[80:95], v[224:227], v[236:239], v[80:95]
	v_mfma_f32_32x32x16_bf16 v[64:79], v[224:227], v[240:243], v[64:79]
	ds_read_b128 v[244:247], v169 offset:49152
	ds_read_b128 v[248:251], v169 offset:53248
	ds_read_b128 v[224:227], v165
	s_waitcnt lgkmcnt(4)
	v_mfma_f32_32x32x16_bf16 v[48:63], v[228:231], v[236:239], v[48:63]
	v_mfma_f32_32x32x16_bf16 v[32:47], v[228:231], v[240:243], v[32:47]
	ds_read_b128 v[228:231], v165 offset:4096
	s_waitcnt lgkmcnt(4)
	v_mfma_f32_32x32x16_bf16 v[16:31], v[232:235], v[236:239], v[16:31]
	v_mfma_f32_32x32x16_bf16 v[0:15], v[232:235], v[240:243], v[0:15]
	ds_read_b128 v[232:235], v165 offset:8192
	s_waitcnt lgkmcnt(2)
	v_mfma_f32_32x32x16_bf16 v[80:95], v[224:227], v[244:247], v[80:95]
	v_mfma_f32_32x32x16_bf16 v[64:79], v[224:227], v[248:251], v[64:79]
	s_waitcnt lgkmcnt(0)
	s_waitcnt vmcnt(0)
	s_barrier
	ds_read_b128 v[236:239], v170
	ds_read_b128 v[240:243], v170 offset:4096
	ds_read_b128 v[224:227], v162 offset:24576
	v_mfma_f32_32x32x16_bf16 v[48:63], v[228:231], v[244:247], v[48:63]
	v_mfma_f32_32x32x16_bf16 v[32:47], v[228:231], v[248:251], v[32:47]
	ds_read_b128 v[228:231], v162 offset:28672
	v_mfma_f32_32x32x16_bf16 v[16:31], v[232:235], v[244:247], v[16:31]
	v_mfma_f32_32x32x16_bf16 v[0:15], v[232:235], v[248:251], v[0:15]
	s_cmp_eq_u32 s15, 14
	s_cbranch_scc1 .Lga_last
; template <int EPI, int MI>
; DI void gemm_tile(const GemmDesc& g, int tm, int tn, char* smem) {
;     ...
;   const int rowA = wm * (32 * MI) + r, rowB = wn * 64 + r;
;   const int hk = hh ^ ((r & 7) ^ ((r >> 3) & 3));
;     ...
;   G_GLDS(0, 0);
;   asm volatile("s_waitcnt vmcnt(0)" ::: "memory");
;   __syncthreads();
;   for (int kt = 0; kt < nk; kt += 2) {
;     if (kt + 1 < nk) G_GLDS(kt + 1, 1);
;     G_COMPUTE(0);
;     asm volatile("s_waitcnt vmcnt(0)" ::: "memory");
;     __syncthreads();
;     if (kt + 1 < nk) {
;       if (kt + 2 < nk) G_GLDS(kt + 2, 0);
;       G_COMPUTE(1);
;       asm volatile("s_waitcnt vmcnt(0)" ::: "memory");
;       __syncthreads();
;     }
;   }
	ds_read_b128 v[232:235], v162 offset:32768
	s_waitcnt lgkmcnt(2)
	v_mfma_f32_32x32x16_bf16 v[80:95], v[224:227], v[236:239], v[80:95]
	v_mfma_f32_32x32x16_bf16 v[64:79], v[224:227], v[240:243], v[64:79]
	s_mov_b32 m0, s100
	v_lshl_add_u64 v[106:107], v[174:175], 0, s[96:97]
	global_load_lds_dwordx4 v[106:107], off
	s_add_u32 m0, s100, 0x1000
	v_lshl_add_u64 v[106:107], v[174:175], 0, s[50:51]
	global_load_lds_dwordx4 v[106:107], off
	s_add_u32 m0, s100, 0x2000
	v_lshl_add_u64 v[106:107], v[174:175], 0, s[24:25]
	global_load_lds_dwordx4 v[106:107], off
	ds_read_b128 v[244:247], v171
	ds_read_b128 v[248:251], v171 offset:4096
	ds_read_b128 v[224:227], v163 offset:24576
	s_waitcnt lgkmcnt(4)
	v_mfma_f32_32x32x16_bf16 v[48:63], v[228:231], v[236:239], v[48:63]
	v_mfma_f32_32x32x16_bf16 v[32:47], v[228:231], v[240:243], v[32:47]
	s_add_u32 m0, s100, 0x3000
	v_lshl_add_u64 v[106:107], v[174:175], 0, s[26:27]
	global_load_lds_dwordx4 v[106:107], off
	s_add_u32 m0, s100, 0x4000
	v_lshl_add_u64 v[106:107], v[174:175], 0, s[28:29]
	global_load_lds_dwordx4 v[106:107], off
	s_add_u32 m0, s100, 0x5000
	v_lshl_add_u64 v[106:107], v[174:175], 0, s[30:31]
	global_load_lds_dwordx4 v[106:107], off
	v_lshl_add_u64 v[174:175], v[174:175], 0, s[18:19]
	ds_read_b128 v[228:231], v163 offset:28672
	s_waitcnt lgkmcnt(4)
	v_mfma_f32_32x32x16_bf16 v[16:31], v[232:235], v[236:239], v[16:31]
	v_mfma_f32_32x32x16_bf16 v[0:15], v[232:235], v[240:243], v[0:15]
	s_add_u32 m0, s100, 0xc000
	v_lshl_add_u64 v[106:107], v[176:177], 0, s[18:19]
	global_load_lds_dwordx4 v[106:107], off
	s_add_u32 m0, s100, 0xd000
	v_lshl_add_u64 v[106:107], v[176:177], 0, s[42:43]
	global_load_lds_dwordx4 v[106:107], off
	s_mov_b64 s[16:17], 0x20080
	s_add_u32 m0, s100, 0xe000
	v_lshl_add_u64 v[106:107], v[176:177], 0, s[16:17]
	global_load_lds_dwordx4 v[106:107], off
	ds_read_b128 v[232:235], v163 offset:32768
	s_waitcnt lgkmcnt(2)
	v_mfma_f32_32x32x16_bf16 v[80:95], v[224:227], v[244:247], v[80:95]
	v_mfma_f32_32x32x16_bf16 v[64:79], v[224:227], v[248:251], v[64:79]
	s_mov_b64 s[16:17], 0x30080
	s_add_u32 m0, s100, 0xf000
	v_lshl_add_u64 v[106:107], v[176:177], 0, s[16:17]
	global_load_lds_dwordx4 v[106:107], off
	v_lshl_add_u64 v[176:177], v[176:177], 0, s[18:19]
	ds_read_b128 v[236:239], v172
	ds_read_b128 v[240:243], v172 offset:4096
	ds_read_b128 v[224:227], v164 offset:24576
	s_waitcnt lgkmcnt(4)
	v_mfma_f32_32x32x16_bf16 v[48:63], v[228:231], v[244:247], v[48:63]
	v_mfma_f32_32x32x16_bf16 v[32:47], v[228:231], v[248:251], v[32:47]
	ds_read_b128 v[228:231], v164 offset:28672
	s_waitcnt lgkmcnt(4)
	v_mfma_f32_32x32x16_bf16 v[16:31], v[232:235], v[244:247], v[16:31]
	v_mfma_f32_32x32x16_bf16 v[0:15], v[232:235], v[248:251], v[0:15]
	ds_read_b128 v[232:235], v164 offset:32768
	s_waitcnt lgkmcnt(2)
	v_mfma_f32_32x32x16_bf16 v[80:95], v[224:227], v[236:239], v[80:95]
	v_mfma_f32_32x32x16_bf16 v[64:79], v[224:227], v[240:243], v[64:79]
	ds_read_b128 v[244:247], v173
	ds_read_b128 v[248:251], v173 offset:4096
	ds_read_b128 v[224:227], v165 offset:24576
	s_waitcnt lgkmcnt(4)
	v_mfma_f32_32x32x16_bf16 v[48:63], v[228:231], v[236:239], v[48:63]
	v_mfma_f32_32x32x16_bf16 v[32:47], v[228:231], v[240:243], v[32:47]
	ds_read_b128 v[228:231], v165 offset:28672
	s_waitcnt lgkmcnt(4)
	v_mfma_f32_32x32x16_bf16 v[16:31], v[232:235], v[236:239], v[16:31]
	v_mfma_f32_32x32x16_bf16 v[0:15], v[232:235], v[240:243], v[0:15]
	ds_read_b128 v[232:235], v165 offset:32768
	s_waitcnt lgkmcnt(2)
	v_mfma_f32_32x32x16_bf16 v[80:95], v[224:227], v[244:247], v[80:95]
	v_mfma_f32_32x32x16_bf16 v[64:79], v[224:227], v[248:251], v[64:79]
	s_waitcnt lgkmcnt(0)
	s_waitcnt vmcnt(0)
	s_barrier
	ds_read_b128 v[236:239], v166 offset:49152
	ds_read_b128 v[240:243], v166 offset:53248
	ds_read_b128 v[224:227], v162
	v_mfma_f32_32x32x16_bf16 v[48:63], v[228:231], v[244:247], v[48:63]
	v_mfma_f32_32x32x16_bf16 v[32:47], v[228:231], v[248:251], v[32:47]
	ds_read_b128 v[228:231], v162 offset:4096
	v_mfma_f32_32x32x16_bf16 v[16:31], v[232:235], v[244:247], v[16:31]
	v_mfma_f32_32x32x16_bf16 v[0:15], v[232:235], v[248:251], v[0:15]
	s_add_u32 s15, s15, 2
	s_branch .Lga_loop

; template <int EPI, int MI>
; DI void gemm_tile(const GemmDesc& g, int tm, int tn, char* smem) {
;     ...
;   const int rowA = wm * (32 * MI) + r, rowB = wn * 64 + r;
;   const int hk = hh ^ ((r & 7) ^ ((r >> 3) & 3));
;     ...
;   G_GLDS(0, 0);
;   asm volatile("s_waitcnt vmcnt(0)" ::: "memory");
;   __syncthreads();
;   for (int kt = 0; kt < nk; kt += 2) {
;     if (kt + 1 < nk) G_GLDS(kt + 1, 1);
;     G_COMPUTE(0);
;     asm volatile("s_waitcnt vmcnt(0)" ::: "memory");
;     __syncthreads();
;     if (kt + 1 < nk) {
;       if (kt + 2 < nk) G_GLDS(kt + 2, 0);
;       G_COMPUTE(1);
;       asm volatile("s_waitcnt vmcnt(0)" ::: "memory");
;       __syncthreads();
;     }
;   }
.Lgd_loop:
	ds_read_b128 v[232:235], v162 offset:8192
	s_waitcnt lgkmcnt(2)
	v_mfma_f32_32x32x16_bf16 v[80:95], v[224:227], v[236:239], v[80:95]
	v_mfma_f32_32x32x16_bf16 v[64:79], v[224:227], v[240:243], v[64:79]
	s_mov_b64 s[16:17], 0x5872080
	s_add_u32 m0, s100, 0x6000
	v_lshl_add_u64 v[106:107], v[252:253], 0, s[16:17]
	global_load_lds_dwordx4 v[106:107], off
	s_mov_b64 s[16:17], 0x589e080
	s_add_u32 m0, s100, 0x7000
	v_lshl_add_u64 v[106:107], v[252:253], 0, s[16:17]
	global_load_lds_dwordx4 v[106:107], off
	s_mov_b64 s[16:17], 0x58ca080
	s_add_u32 m0, s100, 0x8000
	v_lshl_add_u64 v[106:107], v[252:253], 0, s[16:17]
	global_load_lds_dwordx4 v[106:107], off
	ds_read_b128 v[244:247], v167 offset:49152
	ds_read_b128 v[248:251], v167 offset:53248
	ds_read_b128 v[224:227], v163
	s_waitcnt lgkmcnt(4)
	v_mfma_f32_32x32x16_bf16 v[48:63], v[228:231], v[236:239], v[48:63]
	v_mfma_f32_32x32x16_bf16 v[32:47], v[228:231], v[240:243], v[32:47]
	s_mov_b64 s[16:17], 0x58f6080
	s_add_u32 m0, s100, 0x9000
	v_lshl_add_u64 v[106:107], v[252:253], 0, s[16:17]
	global_load_lds_dwordx4 v[106:107], off
	s_mov_b64 s[16:17], 0x5922080
	s_add_u32 m0, s100, 0xa000
	v_lshl_add_u64 v[106:107], v[252:253], 0, s[16:17]
	global_load_lds_dwordx4 v[106:107], off
	s_mov_b64 s[16:17], 0x594e080
	s_add_u32 m0, s100, 0xb000
	v_lshl_add_u64 v[106:107], v[252:253], 0, s[16:17]
	global_load_lds_dwordx4 v[106:107], off
	v_lshl_add_u64 v[252:253], v[252:253], 0, s[4:5]
	ds_read_b128 v[228:231], v163 offset:4096
	s_waitcnt lgkmcnt(4)
	v_mfma_f32_32x32x16_bf16 v[16:31], v[232:235], v[236:239], v[16:31]
	v_mfma_f32_32x32x16_bf16 v[0:15], v[232:235], v[240:243], v[0:15]
	s_mov_b64 s[16:17], 0x1600080
	s_add_u32 m0, s100, 0x10000
	v_lshl_add_u64 v[106:107], v[254:255], 0, s[16:17]
	global_load_lds_dwordx4 v[106:107], off
	s_mov_b64 s[16:17], 0x162c080
	s_add_u32 m0, s100, 0x11000
	v_lshl_add_u64 v[106:107], v[254:255], 0, s[16:17]
	global_load_lds_dwordx4 v[106:107], off
	s_mov_b64 s[16:17], 0x1658080
	s_add_u32 m0, s100, 0x12000
	v_lshl_add_u64 v[106:107], v[254:255], 0, s[16:17]
	global_load_lds_dwordx4 v[106:107], off
	ds_read_b128 v[232:235], v163 offset:8192
	s_waitcnt lgkmcnt(2)
	v_mfma_f32_32x32x16_bf16 v[80:95], v[224:227], v[244:247], v[80:95]
	v_mfma_f32_32x32x16_bf16 v[64:79], v[224:227], v[248:251], v[64:79]
	s_mov_b64 s[16:17], 0x1684080
	s_add_u32 m0, s100, 0x13000
	v_lshl_add_u64 v[106:107], v[254:255], 0, s[16:17]
	global_load_lds_dwordx4 v[106:107], off
	v_lshl_add_u64 v[254:255], v[254:255], 0, s[4:5]
	ds_read_b128 v[236:239], v168 offset:49152
	ds_read_b128 v[240:243], v168 offset:53248
	ds_read_b128 v[224:227], v164
	s_waitcnt lgkmcnt(4)
	v_mfma_f32_32x32x16_bf16 v[48:63], v[228:231], v[244:247], v[48:63]
	v_mfma_f32_32x32x16_bf16 v[32:47], v[228:231], v[248:251], v[32:47]
	ds_read_b128 v[228:231], v164 offset:4096
	s_waitcnt lgkmcnt(4)
	v_mfma_f32_32x32x16_bf16 v[16:31], v[232:235], v[244:247], v[16:31]
	v_mfma_f32_32x32x16_bf16 v[0:15], v[232:235], v[248:251], v[0:15]
	ds_read_b128 v[232:235], v164 offset:8192
	s_waitcnt lgkmcnt(2)
	v_mfma_f32_32x32x16_bf16 v[80:95], v[224:227], v[236:239], v[80:95]
	v_mfma_f32_32x32x16_bf16 v[64:79], v[224:227], v[240:243], v[64:79]
	ds_read_b128 v[244:247], v169 offset:49152
	ds_read_b128 v[248:251], v169 offset:53248
	ds_read_b128 v[224:227], v165
	s_waitcnt lgkmcnt(4)
	v_mfma_f32_32x32x16_bf16 v[48:63], v[228:231], v[236:239], v[48:63]
	v_mfma_f32_32x32x16_bf16 v[32:47], v[228:231], v[240:243], v[32:47]
	ds_read_b128 v[228:231], v165 offset:4096
	s_waitcnt lgkmcnt(4)
	v_mfma_f32_32x32x16_bf16 v[16:31], v[232:235], v[236:239], v[16:31]
	v_mfma_f32_32x32x16_bf16 v[0:15], v[232:235], v[240:243], v[0:15]
	ds_read_b128 v[232:235], v165 offset:8192
	s_waitcnt lgkmcnt(2)
	v_mfma_f32_32x32x16_bf16 v[80:95], v[224:227], v[244:247], v[80:95]
	v_mfma_f32_32x32x16_bf16 v[64:79], v[224:227], v[248:251], v[64:79]
	s_waitcnt lgkmcnt(0)
	s_waitcnt vmcnt(0)
	s_barrier
	ds_read_b128 v[236:239], v170
	ds_read_b128 v[240:243], v170 offset:4096
	ds_read_b128 v[224:227], v162 offset:24576
	v_mfma_f32_32x32x16_bf16 v[48:63], v[228:231], v[244:247], v[48:63]
	v_mfma_f32_32x32x16_bf16 v[32:47], v[228:231], v[248:251], v[32:47]
	ds_read_b128 v[228:231], v162 offset:28672
	v_mfma_f32_32x32x16_bf16 v[16:31], v[232:235], v[244:247], v[16:31]
	v_mfma_f32_32x32x16_bf16 v[0:15], v[232:235], v[248:251], v[0:15]
	s_cmp_eq_u32 s15, 42
	s_cbranch_scc1 .Lgd_last
; template <int EPI, int MI>
; DI void gemm_tile(const GemmDesc& g, int tm, int tn, char* smem) {
;     ...
;   const int rowA = wm * (32 * MI) + r, rowB = wn * 64 + r;
;   const int hk = hh ^ ((r & 7) ^ ((r >> 3) & 3));
;     ...
;   G_GLDS(0, 0);
;   asm volatile("s_waitcnt vmcnt(0)" ::: "memory");
;   __syncthreads();
;   for (int kt = 0; kt < nk; kt += 2) {
;     if (kt + 1 < nk) G_GLDS(kt + 1, 1);
;     G_COMPUTE(0);
;     asm volatile("s_waitcnt vmcnt(0)" ::: "memory");
;     __syncthreads();
;     if (kt + 1 < nk) {
;       if (kt + 2 < nk) G_GLDS(kt + 2, 0);
;       G_COMPUTE(1);
;       asm volatile("s_waitcnt vmcnt(0)" ::: "memory");
;       __syncthreads();
;     }
;   }
	ds_read_b128 v[232:235], v162 offset:32768
	s_waitcnt lgkmcnt(2)
	v_mfma_f32_32x32x16_bf16 v[80:95], v[224:227], v[236:239], v[80:95]
	v_mfma_f32_32x32x16_bf16 v[64:79], v[224:227], v[240:243], v[64:79]
	s_mov_b64 s[16:17], 0x5872080
	s_mov_b32 m0, s100
	v_lshl_add_u64 v[106:107], v[252:253], 0, s[16:17]
	global_load_lds_dwordx4 v[106:107], off
	s_mov_b64 s[16:17], 0x589e080
	s_add_u32 m0, s100, 0x1000
	v_lshl_add_u64 v[106:107], v[252:253], 0, s[16:17]
	global_load_lds_dwordx4 v[106:107], off
	s_mov_b64 s[16:17], 0x58ca080
	s_add_u32 m0, s100, 0x2000
	v_lshl_add_u64 v[106:107], v[252:253], 0, s[16:17]
	global_load_lds_dwordx4 v[106:107], off
	ds_read_b128 v[244:247], v171
	ds_read_b128 v[248:251], v171 offset:4096
	ds_read_b128 v[224:227], v163 offset:24576
	s_waitcnt lgkmcnt(4)
	v_mfma_f32_32x32x16_bf16 v[48:63], v[228:231], v[236:239], v[48:63]
	v_mfma_f32_32x32x16_bf16 v[32:47], v[228:231], v[240:243], v[32:47]
	s_mov_b64 s[16:17], 0x58f6080
	s_add_u32 m0, s100, 0x3000
	v_lshl_add_u64 v[106:107], v[252:253], 0, s[16:17]
	global_load_lds_dwordx4 v[106:107], off
	s_mov_b64 s[16:17], 0x5922080
	s_add_u32 m0, s100, 0x4000
	v_lshl_add_u64 v[106:107], v[252:253], 0, s[16:17]
	global_load_lds_dwordx4 v[106:107], off
	s_mov_b64 s[16:17], 0x594e080
	s_add_u32 m0, s100, 0x5000
	v_lshl_add_u64 v[106:107], v[252:253], 0, s[16:17]
	global_load_lds_dwordx4 v[106:107], off
	v_lshl_add_u64 v[252:253], v[252:253], 0, s[4:5]
	ds_read_b128 v[228:231], v163 offset:28672
	s_waitcnt lgkmcnt(4)
	v_mfma_f32_32x32x16_bf16 v[16:31], v[232:235], v[236:239], v[16:31]
	v_mfma_f32_32x32x16_bf16 v[0:15], v[232:235], v[240:243], v[0:15]
	s_mov_b64 s[16:17], 0x1600080
	s_add_u32 m0, s100, 0xc000
	v_lshl_add_u64 v[106:107], v[254:255], 0, s[16:17]
	global_load_lds_dwordx4 v[106:107], off
	s_mov_b64 s[16:17], 0x162c080
	s_add_u32 m0, s100, 0xd000
	v_lshl_add_u64 v[106:107], v[254:255], 0, s[16:17]
	global_load_lds_dwordx4 v[106:107], off
	s_mov_b64 s[16:17], 0x1658080
	s_add_u32 m0, s100, 0xe000
	v_lshl_add_u64 v[106:107], v[254:255], 0, s[16:17]
	global_load_lds_dwordx4 v[106:107], off
	ds_read_b128 v[232:235], v163 offset:32768
	s_waitcnt lgkmcnt(2)
	v_mfma_f32_32x32x16_bf16 v[80:95], v[224:227], v[244:247], v[80:95]
	v_mfma_f32_32x32x16_bf16 v[64:79], v[224:227], v[248:251], v[64:79]
	s_mov_b64 s[16:17], 0x1684080
	s_add_u32 m0, s100, 0xf000
	v_lshl_add_u64 v[106:107], v[254:255], 0, s[16:17]
	global_load_lds_dwordx4 v[106:107], off
	v_lshl_add_u64 v[254:255], v[254:255], 0, s[4:5]
	ds_read_b128 v[236:239], v172
	ds_read_b128 v[240:243], v172 offset:4096
	ds_read_b128 v[224:227], v164 offset:24576
	s_waitcnt lgkmcnt(4)
	v_mfma_f32_32x32x16_bf16 v[48:63], v[228:231], v[244:247], v[48:63]
	v_mfma_f32_32x32x16_bf16 v[32:47], v[228:231], v[248:251], v[32:47]
	ds_read_b128 v[228:231], v164 offset:28672
	s_waitcnt lgkmcnt(4)
	v_mfma_f32_32x32x16_bf16 v[16:31], v[232:235], v[244:247], v[16:31]
	v_mfma_f32_32x32x16_bf16 v[0:15], v[232:235], v[248:251], v[0:15]
	ds_read_b128 v[232:235], v164 offset:32768
	s_waitcnt lgkmcnt(2)
	v_mfma_f32_32x32x16_bf16 v[80:95], v[224:227], v[236:239], v[80:95]
	v_mfma_f32_32x32x16_bf16 v[64:79], v[224:227], v[240:243], v[64:79]
	ds_read_b128 v[244:247], v173
	ds_read_b128 v[248:251], v173 offset:4096
	ds_read_b128 v[224:227], v165 offset:24576
	s_waitcnt lgkmcnt(4)
	v_mfma_f32_32x32x16_bf16 v[48:63], v[228:231], v[236:239], v[48:63]
	v_mfma_f32_32x32x16_bf16 v[32:47], v[228:231], v[240:243], v[32:47]
	ds_read_b128 v[228:231], v165 offset:28672
	s_waitcnt lgkmcnt(4)
	v_mfma_f32_32x32x16_bf16 v[16:31], v[232:235], v[236:239], v[16:31]
	v_mfma_f32_32x32x16_bf16 v[0:15], v[232:235], v[240:243], v[0:15]
	ds_read_b128 v[232:235], v165 offset:32768
	s_waitcnt lgkmcnt(2)
	v_mfma_f32_32x32x16_bf16 v[80:95], v[224:227], v[244:247], v[80:95]
	v_mfma_f32_32x32x16_bf16 v[64:79], v[224:227], v[248:251], v[64:79]
	s_waitcnt lgkmcnt(0)
	s_waitcnt vmcnt(0)
	s_barrier
	ds_read_b128 v[236:239], v166 offset:49152
	ds_read_b128 v[240:243], v166 offset:53248
	ds_read_b128 v[224:227], v162
	v_mfma_f32_32x32x16_bf16 v[48:63], v[228:231], v[244:247], v[48:63]
	v_mfma_f32_32x32x16_bf16 v[32:47], v[228:231], v[248:251], v[32:47]
	ds_read_b128 v[228:231], v162 offset:4096
	v_mfma_f32_32x32x16_bf16 v[16:31], v[232:235], v[244:247], v[16:31]
	v_mfma_f32_32x32x16_bf16 v[0:15], v[232:235], v[248:251], v[0:15]
	s_add_u32 s15, s15, 2
	s_branch .Lgd_loop

; template <int EPI, int MI>
; DI void gemm_tile(const GemmDesc& g, int tm, int tn, char* smem) {
;     ...
;   const int rowA = wm * (32 * MI) + r, rowB = wn * 64 + r;
;   const int hk = hh ^ ((r & 7) ^ ((r >> 3) & 3));
;     ...
;   G_GLDS(0, 0);
;   asm volatile("s_waitcnt vmcnt(0)" ::: "memory");
;   __syncthreads();
;   for (int kt = 0; kt < nk; kt += 2) {
;     if (kt + 1 < nk) G_GLDS(kt + 1, 1);
;     G_COMPUTE(0);
;     asm volatile("s_waitcnt vmcnt(0)" ::: "memory");
;     __syncthreads();
;     if (kt + 1 < nk) {
;       if (kt + 2 < nk) G_GLDS(kt + 2, 0);
;       G_COMPUTE(1);
;       asm volatile("s_waitcnt vmcnt(0)" ::: "memory");
;       __syncthreads();
;     }
;   }
.Lgw_loop:
	ds_read_b128 v[232:235], v162 offset:8192
	s_waitcnt lgkmcnt(2)
	v_mfma_f32_32x32x16_bf16 v[80:95], v[224:227], v[236:239], v[80:95]
	v_mfma_f32_32x32x16_bf16 v[64:79], v[224:227], v[240:243], v[64:79]
	s_add_u32 m0, s100, 0x6000
	v_lshl_add_u64 v[106:107], v[252:253], 0, s[96:97]
	global_load_lds_dwordx4 v[106:107], off
	s_add_u32 m0, s100, 0x7000
	v_lshl_add_u64 v[106:107], v[252:253], 0, s[50:51]
	global_load_lds_dwordx4 v[106:107], off
	s_add_u32 m0, s100, 0x8000
	v_lshl_add_u64 v[106:107], v[252:253], 0, s[24:25]
	global_load_lds_dwordx4 v[106:107], off
	ds_read_b128 v[244:247], v167 offset:49152
	ds_read_b128 v[248:251], v167 offset:53248
	ds_read_b128 v[224:227], v163
	s_waitcnt lgkmcnt(4)
	v_mfma_f32_32x32x16_bf16 v[48:63], v[228:231], v[236:239], v[48:63]
	v_mfma_f32_32x32x16_bf16 v[32:47], v[228:231], v[240:243], v[32:47]
	s_add_u32 m0, s100, 0x9000
	v_lshl_add_u64 v[106:107], v[252:253], 0, s[26:27]
	global_load_lds_dwordx4 v[106:107], off
	s_add_u32 m0, s100, 0xa000
	v_lshl_add_u64 v[106:107], v[252:253], 0, s[28:29]
	global_load_lds_dwordx4 v[106:107], off
	s_add_u32 m0, s100, 0xb000
	v_lshl_add_u64 v[106:107], v[252:253], 0, s[30:31]
	global_load_lds_dwordx4 v[106:107], off
	v_lshl_add_u64 v[252:253], v[252:253], 0, s[0:1]
	ds_read_b128 v[228:231], v163 offset:4096
	s_waitcnt lgkmcnt(4)
	v_mfma_f32_32x32x16_bf16 v[16:31], v[232:235], v[236:239], v[16:31]
	v_mfma_f32_32x32x16_bf16 v[0:15], v[232:235], v[240:243], v[0:15]
	s_mov_b64 s[16:17], 0x2100080
	s_add_u32 m0, s100, 0x10000
	v_lshl_add_u64 v[106:107], v[254:255], 0, s[16:17]
	global_load_lds_dwordx4 v[106:107], off
	s_mov_b64 s[16:17], 0x2110080
	s_add_u32 m0, s100, 0x11000
	v_lshl_add_u64 v[106:107], v[254:255], 0, s[16:17]
	global_load_lds_dwordx4 v[106:107], off
	s_mov_b64 s[16:17], 0x2120080
	s_add_u32 m0, s100, 0x12000
	v_lshl_add_u64 v[106:107], v[254:255], 0, s[16:17]
	global_load_lds_dwordx4 v[106:107], off
	ds_read_b128 v[232:235], v163 offset:8192
	s_waitcnt lgkmcnt(2)
	v_mfma_f32_32x32x16_bf16 v[80:95], v[224:227], v[244:247], v[80:95]
	v_mfma_f32_32x32x16_bf16 v[64:79], v[224:227], v[248:251], v[64:79]
	s_mov_b64 s[16:17], 0x2130080
	s_add_u32 m0, s100, 0x13000
	v_lshl_add_u64 v[106:107], v[254:255], 0, s[16:17]
	global_load_lds_dwordx4 v[106:107], off
	v_lshl_add_u64 v[254:255], v[254:255], 0, s[0:1]
	ds_read_b128 v[236:239], v168 offset:49152
	ds_read_b128 v[240:243], v168 offset:53248
	ds_read_b128 v[224:227], v164
	s_waitcnt lgkmcnt(4)
	v_mfma_f32_32x32x16_bf16 v[48:63], v[228:231], v[244:247], v[48:63]
	v_mfma_f32_32x32x16_bf16 v[32:47], v[228:231], v[248:251], v[32:47]
	ds_read_b128 v[228:231], v164 offset:4096
	s_waitcnt lgkmcnt(4)
	v_mfma_f32_32x32x16_bf16 v[16:31], v[232:235], v[244:247], v[16:31]
	v_mfma_f32_32x32x16_bf16 v[0:15], v[232:235], v[248:251], v[0:15]
	ds_read_b128 v[232:235], v164 offset:8192
	s_waitcnt lgkmcnt(2)
	v_mfma_f32_32x32x16_bf16 v[80:95], v[224:227], v[236:239], v[80:95]
	v_mfma_f32_32x32x16_bf16 v[64:79], v[224:227], v[240:243], v[64:79]
	ds_read_b128 v[244:247], v169 offset:49152
	ds_read_b128 v[248:251], v169 offset:53248
	ds_read_b128 v[224:227], v165
	s_waitcnt lgkmcnt(4)
	v_mfma_f32_32x32x16_bf16 v[48:63], v[228:231], v[236:239], v[48:63]
	v_mfma_f32_32x32x16_bf16 v[32:47], v[228:231], v[240:243], v[32:47]
	ds_read_b128 v[228:231], v165 offset:4096
	s_waitcnt lgkmcnt(4)
	v_mfma_f32_32x32x16_bf16 v[16:31], v[232:235], v[236:239], v[16:31]
	v_mfma_f32_32x32x16_bf16 v[0:15], v[232:235], v[240:243], v[0:15]
	ds_read_b128 v[232:235], v165 offset:8192
	s_waitcnt lgkmcnt(2)
	v_mfma_f32_32x32x16_bf16 v[80:95], v[224:227], v[244:247], v[80:95]
	v_mfma_f32_32x32x16_bf16 v[64:79], v[224:227], v[248:251], v[64:79]
	s_waitcnt lgkmcnt(0)
	s_waitcnt vmcnt(0)
	s_barrier
	ds_read_b128 v[236:239], v170
	ds_read_b128 v[240:243], v170 offset:4096
	ds_read_b128 v[224:227], v162 offset:24576
	v_mfma_f32_32x32x16_bf16 v[48:63], v[228:231], v[244:247], v[48:63]
	v_mfma_f32_32x32x16_bf16 v[32:47], v[228:231], v[248:251], v[32:47]
	ds_read_b128 v[228:231], v162 offset:28672
	v_mfma_f32_32x32x16_bf16 v[16:31], v[232:235], v[244:247], v[16:31]
	v_mfma_f32_32x32x16_bf16 v[0:15], v[232:235], v[248:251], v[0:15]
	s_cmp_eq_u32 s101, 14
	s_cbranch_scc1 .Lgw_last
; template <int EPI, int MI>
; DI void gemm_tile(const GemmDesc& g, int tm, int tn, char* smem) {
;     ...
;   const int rowA = wm * (32 * MI) + r, rowB = wn * 64 + r;
;   const int hk = hh ^ ((r & 7) ^ ((r >> 3) & 3));
;     ...
;   G_GLDS(0, 0);
;   asm volatile("s_waitcnt vmcnt(0)" ::: "memory");
;   __syncthreads();
;   for (int kt = 0; kt < nk; kt += 2) {
;     if (kt + 1 < nk) G_GLDS(kt + 1, 1);
;     G_COMPUTE(0);
;     asm volatile("s_waitcnt vmcnt(0)" ::: "memory");
;     __syncthreads();
;     if (kt + 1 < nk) {
;       if (kt + 2 < nk) G_GLDS(kt + 2, 0);
;       G_COMPUTE(1);
;       asm volatile("s_waitcnt vmcnt(0)" ::: "memory");
;       __syncthreads();
;     }
;   }
	ds_read_b128 v[232:235], v162 offset:32768
	s_waitcnt lgkmcnt(2)
	v_mfma_f32_32x32x16_bf16 v[80:95], v[224:227], v[236:239], v[80:95]
	v_mfma_f32_32x32x16_bf16 v[64:79], v[224:227], v[240:243], v[64:79]
	s_mov_b32 m0, s100
	v_lshl_add_u64 v[106:107], v[252:253], 0, s[96:97]
	global_load_lds_dwordx4 v[106:107], off
	s_add_u32 m0, s100, 0x1000
	v_lshl_add_u64 v[106:107], v[252:253], 0, s[50:51]
	global_load_lds_dwordx4 v[106:107], off
	s_add_u32 m0, s100, 0x2000
	v_lshl_add_u64 v[106:107], v[252:253], 0, s[24:25]
	global_load_lds_dwordx4 v[106:107], off
	ds_read_b128 v[244:247], v171
	ds_read_b128 v[248:251], v171 offset:4096
	ds_read_b128 v[224:227], v163 offset:24576
	s_waitcnt lgkmcnt(4)
	v_mfma_f32_32x32x16_bf16 v[48:63], v[228:231], v[236:239], v[48:63]
	v_mfma_f32_32x32x16_bf16 v[32:47], v[228:231], v[240:243], v[32:47]
	s_add_u32 m0, s100, 0x3000
	v_lshl_add_u64 v[106:107], v[252:253], 0, s[26:27]
	global_load_lds_dwordx4 v[106:107], off
	s_add_u32 m0, s100, 0x4000
	v_lshl_add_u64 v[106:107], v[252:253], 0, s[28:29]
	global_load_lds_dwordx4 v[106:107], off
	s_add_u32 m0, s100, 0x5000
	v_lshl_add_u64 v[106:107], v[252:253], 0, s[30:31]
	global_load_lds_dwordx4 v[106:107], off
	v_lshl_add_u64 v[252:253], v[252:253], 0, s[0:1]
	ds_read_b128 v[228:231], v163 offset:28672
	s_waitcnt lgkmcnt(4)
	v_mfma_f32_32x32x16_bf16 v[16:31], v[232:235], v[236:239], v[16:31]
	v_mfma_f32_32x32x16_bf16 v[0:15], v[232:235], v[240:243], v[0:15]
	s_mov_b64 s[16:17], 0x2100080
	s_add_u32 m0, s100, 0xc000
	v_lshl_add_u64 v[106:107], v[254:255], 0, s[16:17]
	global_load_lds_dwordx4 v[106:107], off
	s_mov_b64 s[16:17], 0x2110080
	s_add_u32 m0, s100, 0xd000
	v_lshl_add_u64 v[106:107], v[254:255], 0, s[16:17]
	global_load_lds_dwordx4 v[106:107], off
	s_mov_b64 s[16:17], 0x2120080
	s_add_u32 m0, s100, 0xe000
	v_lshl_add_u64 v[106:107], v[254:255], 0, s[16:17]
	global_load_lds_dwordx4 v[106:107], off
	ds_read_b128 v[232:235], v163 offset:32768
	s_waitcnt lgkmcnt(2)
	v_mfma_f32_32x32x16_bf16 v[80:95], v[224:227], v[244:247], v[80:95]
	v_mfma_f32_32x32x16_bf16 v[64:79], v[224:227], v[248:251], v[64:79]
	s_mov_b64 s[16:17], 0x2130080
	s_add_u32 m0, s100, 0xf000
	v_lshl_add_u64 v[106:107], v[254:255], 0, s[16:17]
	global_load_lds_dwordx4 v[106:107], off
	v_lshl_add_u64 v[254:255], v[254:255], 0, s[0:1]
	ds_read_b128 v[236:239], v172
	ds_read_b128 v[240:243], v172 offset:4096
	ds_read_b128 v[224:227], v164 offset:24576
	s_waitcnt lgkmcnt(4)
	v_mfma_f32_32x32x16_bf16 v[48:63], v[228:231], v[244:247], v[48:63]
	v_mfma_f32_32x32x16_bf16 v[32:47], v[228:231], v[248:251], v[32:47]
	ds_read_b128 v[228:231], v164 offset:28672
	s_waitcnt lgkmcnt(4)
	v_mfma_f32_32x32x16_bf16 v[16:31], v[232:235], v[244:247], v[16:31]
	v_mfma_f32_32x32x16_bf16 v[0:15], v[232:235], v[248:251], v[0:15]
	ds_read_b128 v[232:235], v164 offset:32768
	s_waitcnt lgkmcnt(2)
	v_mfma_f32_32x32x16_bf16 v[80:95], v[224:227], v[236:239], v[80:95]
	v_mfma_f32_32x32x16_bf16 v[64:79], v[224:227], v[240:243], v[64:79]
	ds_read_b128 v[244:247], v173
	ds_read_b128 v[248:251], v173 offset:4096
	ds_read_b128 v[224:227], v165 offset:24576
	s_waitcnt lgkmcnt(4)
	v_mfma_f32_32x32x16_bf16 v[48:63], v[228:231], v[236:239], v[48:63]
	v_mfma_f32_32x32x16_bf16 v[32:47], v[228:231], v[240:243], v[32:47]
	ds_read_b128 v[228:231], v165 offset:28672
	s_waitcnt lgkmcnt(4)
	v_mfma_f32_32x32x16_bf16 v[16:31], v[232:235], v[236:239], v[16:31]
	v_mfma_f32_32x32x16_bf16 v[0:15], v[232:235], v[240:243], v[0:15]
	ds_read_b128 v[232:235], v165 offset:32768
	s_waitcnt lgkmcnt(2)
	v_mfma_f32_32x32x16_bf16 v[80:95], v[224:227], v[244:247], v[80:95]
	v_mfma_f32_32x32x16_bf16 v[64:79], v[224:227], v[248:251], v[64:79]
	s_waitcnt lgkmcnt(0)
	s_waitcnt vmcnt(0)
	s_barrier
	ds_read_b128 v[236:239], v166 offset:49152
	ds_read_b128 v[240:243], v166 offset:53248
	ds_read_b128 v[224:227], v162
	v_mfma_f32_32x32x16_bf16 v[48:63], v[228:231], v[244:247], v[48:63]
	v_mfma_f32_32x32x16_bf16 v[32:47], v[228:231], v[248:251], v[32:47]
	ds_read_b128 v[228:231], v162 offset:4096
	v_mfma_f32_32x32x16_bf16 v[16:31], v[232:235], v[244:247], v[16:31]
	v_mfma_f32_32x32x16_bf16 v[0:15], v[232:235], v[248:251], v[0:15]
	s_add_u32 s101, s101, 2
	s_branch .Lgw_loop

; template <int EPI, int MI>
; DI void gemm_tile(const GemmDesc& g, int tm, int tn, char* smem) {
;     ...
;   const int rowA = wm * (32 * MI) + r, rowB = wn * 64 + r;
;   const int hk = hh ^ ((r & 7) ^ ((r >> 3) & 3));
;     ...
;   G_GLDS(0, 0);
;   asm volatile("s_waitcnt vmcnt(0)" ::: "memory");
;   __syncthreads();
;   for (int kt = 0; kt < nk; kt += 2) {
;     if (kt + 1 < nk) G_GLDS(kt + 1, 1);
;     G_COMPUTE(0);
;     asm volatile("s_waitcnt vmcnt(0)" ::: "memory");
;     __syncthreads();
;     if (kt + 1 < nk) {
;       if (kt + 2 < nk) G_GLDS(kt + 2, 0);
;       G_COMPUTE(1);
;       asm volatile("s_waitcnt vmcnt(0)" ::: "memory");
;       __syncthreads();
;     }
;   }
.Lgc_loop:
	ds_read_b128 v[248:251], v103 offset:32768
	ds_read_b128 v[252:255], v103 offset:36864
	ds_read_b128 v[232:235], v99
	s_waitcnt lgkmcnt(4)
	v_mfma_f32_32x32x16_bf16 v[48:63], v[224:227], v[240:243], v[48:63]
	v_mfma_f32_32x32x16_bf16 v[32:47], v[224:227], v[244:247], v[32:47]
	s_add_u32 m0, s100, 0x4000
	v_lshl_add_u64 v[106:107], v[72:73], 0, s[96:97]
	global_load_lds_dwordx4 v[106:107], off
	s_add_u32 m0, s100, 0x5000
	v_lshl_add_u64 v[106:107], v[72:73], 0, s[50:51]
	global_load_lds_dwordx4 v[106:107], off
	s_add_u32 m0, s100, 0x6000
	v_lshl_add_u64 v[106:107], v[72:73], 0, s[24:25]
	global_load_lds_dwordx4 v[106:107], off
	ds_read_b128 v[236:239], v99 offset:4096
	s_waitcnt lgkmcnt(4)
	v_mfma_f32_32x32x16_bf16 v[16:31], v[228:231], v[240:243], v[16:31]
	v_mfma_f32_32x32x16_bf16 v[0:15], v[228:231], v[244:247], v[0:15]
	s_add_u32 m0, s100, 0x7000
	v_lshl_add_u64 v[106:107], v[72:73], 0, s[26:27]
	global_load_lds_dwordx4 v[106:107], off
	v_lshl_add_u64 v[72:73], v[72:73], 0, s[44:45]
	s_mov_b64 s[0:1], 0xb00080
	s_add_u32 m0, s100, 0xc000
	v_lshl_add_u64 v[106:107], v[74:75], 0, s[0:1]
	global_load_lds_dwordx4 v[106:107], off
	s_mov_b64 s[0:1], 0xb10080
	s_add_u32 m0, s100, 0xd000
	v_lshl_add_u64 v[106:107], v[74:75], 0, s[0:1]
	global_load_lds_dwordx4 v[106:107], off
	ds_read_b128 v[240:243], v104 offset:32768
	ds_read_b128 v[244:247], v104 offset:36864
	ds_read_b128 v[224:227], v100
	s_waitcnt lgkmcnt(4)
	v_mfma_f32_32x32x16_bf16 v[48:63], v[232:235], v[248:251], v[48:63]
	v_mfma_f32_32x32x16_bf16 v[32:47], v[232:235], v[252:255], v[32:47]
	s_mov_b64 s[0:1], 0xb20080
	s_add_u32 m0, s100, 0xe000
	v_lshl_add_u64 v[106:107], v[74:75], 0, s[0:1]
	global_load_lds_dwordx4 v[106:107], off
	s_mov_b64 s[0:1], 0xb30080
	s_add_u32 m0, s100, 0xf000
	v_lshl_add_u64 v[106:107], v[74:75], 0, s[0:1]
	global_load_lds_dwordx4 v[106:107], off
	v_lshl_add_u64 v[74:75], v[74:75], 0, s[44:45]
	ds_read_b128 v[228:231], v100 offset:4096
	s_waitcnt lgkmcnt(4)
	v_mfma_f32_32x32x16_bf16 v[16:31], v[236:239], v[248:251], v[16:31]
	v_mfma_f32_32x32x16_bf16 v[0:15], v[236:239], v[252:255], v[0:15]
	ds_read_b128 v[248:251], v105 offset:32768
	ds_read_b128 v[252:255], v105 offset:36864
	ds_read_b128 v[232:235], v101
	s_waitcnt lgkmcnt(4)
	v_mfma_f32_32x32x16_bf16 v[48:63], v[224:227], v[240:243], v[48:63]
	v_mfma_f32_32x32x16_bf16 v[32:47], v[224:227], v[244:247], v[32:47]
	ds_read_b128 v[236:239], v101 offset:4096
	s_waitcnt lgkmcnt(4)
	v_mfma_f32_32x32x16_bf16 v[16:31], v[228:231], v[240:243], v[16:31]
	v_mfma_f32_32x32x16_bf16 v[0:15], v[228:231], v[244:247], v[0:15]
	s_waitcnt lgkmcnt(0)
	s_waitcnt vmcnt(0)
	s_barrier
	ds_read_b128 v[240:243], v102 offset:49152
	ds_read_b128 v[244:247], v102 offset:53248
	ds_read_b128 v[224:227], v98 offset:16384
	v_mfma_f32_32x32x16_bf16 v[48:63], v[232:235], v[248:251], v[48:63]
	v_mfma_f32_32x32x16_bf16 v[32:47], v[232:235], v[252:255], v[32:47]
	ds_read_b128 v[228:231], v98 offset:20480
	v_mfma_f32_32x32x16_bf16 v[16:31], v[236:239], v[248:251], v[16:31]
	v_mfma_f32_32x32x16_bf16 v[0:15], v[236:239], v[252:255], v[0:15]
	s_cmp_eq_u32 s101, 14
	s_cbranch_scc1 .Lgc_last
	ds_read_b128 v[248:251], v103 offset:49152
	ds_read_b128 v[252:255], v103 offset:53248
	ds_read_b128 v[232:235], v99 offset:16384
	s_waitcnt lgkmcnt(4)
	v_mfma_f32_32x32x16_bf16 v[48:63], v[224:227], v[240:243], v[48:63]
	v_mfma_f32_32x32x16_bf16 v[32:47], v[224:227], v[244:247], v[32:47]
	s_mov_b32 m0, s100
	v_lshl_add_u64 v[106:107], v[72:73], 0, s[96:97]
	global_load_lds_dwordx4 v[106:107], off
	s_add_u32 m0, s100, 0x1000
	v_lshl_add_u64 v[106:107], v[72:73], 0, s[50:51]
	global_load_lds_dwordx4 v[106:107], off
	s_add_u32 m0, s100, 0x2000
	v_lshl_add_u64 v[106:107], v[72:73], 0, s[24:25]
	global_load_lds_dwordx4 v[106:107], off
	ds_read_b128 v[236:239], v99 offset:20480
	s_waitcnt lgkmcnt(4)
	v_mfma_f32_32x32x16_bf16 v[16:31], v[228:231], v[240:243], v[16:31]
	v_mfma_f32_32x32x16_bf16 v[0:15], v[228:231], v[244:247], v[0:15]
	s_add_u32 m0, s100, 0x3000
	v_lshl_add_u64 v[106:107], v[72:73], 0, s[26:27]
	global_load_lds_dwordx4 v[106:107], off
	v_lshl_add_u64 v[72:73], v[72:73], 0, s[44:45]
	s_mov_b64 s[0:1], 0xb00080
	s_add_u32 m0, s100, 0x8000
	v_lshl_add_u64 v[106:107], v[74:75], 0, s[0:1]
	global_load_lds_dwordx4 v[106:107], off
	s_mov_b64 s[0:1], 0xb10080
	s_add_u32 m0, s100, 0x9000
	v_lshl_add_u64 v[106:107], v[74:75], 0, s[0:1]
	global_load_lds_dwordx4 v[106:107], off
	ds_read_b128 v[240:243], v104 offset:49152
	ds_read_b128 v[244:247], v104 offset:53248
	ds_read_b128 v[224:227], v100 offset:16384
	s_waitcnt lgkmcnt(4)
	v_mfma_f32_32x32x16_bf16 v[48:63], v[232:235], v[248:251], v[48:63]
	v_mfma_f32_32x32x16_bf16 v[32:47], v[232:235], v[252:255], v[32:47]
	s_mov_b64 s[0:1], 0xb20080
	s_add_u32 m0, s100, 0xa000
	v_lshl_add_u64 v[106:107], v[74:75], 0, s[0:1]
	global_load_lds_dwordx4 v[106:107], off
	s_mov_b64 s[0:1], 0xb30080
	s_add_u32 m0, s100, 0xb000
	v_lshl_add_u64 v[106:107], v[74:75], 0, s[0:1]
	global_load_lds_dwordx4 v[106:107], off
	v_lshl_add_u64 v[74:75], v[74:75], 0, s[44:45]
	ds_read_b128 v[228:231], v100 offset:20480
	s_waitcnt lgkmcnt(4)
	v_mfma_f32_32x32x16_bf16 v[16:31], v[236:239], v[248:251], v[16:31]
	v_mfma_f32_32x32x16_bf16 v[0:15], v[236:239], v[252:255], v[0:15]
	ds_read_b128 v[248:251], v105 offset:49152
	ds_read_b128 v[252:255], v105 offset:53248
	ds_read_b128 v[232:235], v101 offset:16384
	s_waitcnt lgkmcnt(4)
	v_mfma_f32_32x32x16_bf16 v[48:63], v[224:227], v[240:243], v[48:63]
	v_mfma_f32_32x32x16_bf16 v[32:47], v[224:227], v[244:247], v[32:47]
	ds_read_b128 v[236:239], v101 offset:20480
	s_waitcnt lgkmcnt(4)
	v_mfma_f32_32x32x16_bf16 v[16:31], v[228:231], v[240:243], v[16:31]
	v_mfma_f32_32x32x16_bf16 v[0:15], v[228:231], v[244:247], v[0:15]
	s_waitcnt lgkmcnt(0)
	s_waitcnt vmcnt(0)
	s_barrier
	ds_read_b128 v[240:243], v102 offset:32768
	ds_read_b128 v[244:247], v102 offset:36864
	ds_read_b128 v[224:227], v98
	v_mfma_f32_32x32x16_bf16 v[48:63], v[232:235], v[248:251], v[48:63]
	v_mfma_f32_32x32x16_bf16 v[32:47], v[232:235], v[252:255], v[32:47]
	ds_read_b128 v[228:231], v98 offset:4096
	v_mfma_f32_32x32x16_bf16 v[16:31], v[236:239], v[248:251], v[16:31]
	v_mfma_f32_32x32x16_bf16 v[0:15], v[236:239], v[252:255], v[0:15]
	s_add_u32 s101, s101, 2
	s_branch .Lgc_loop

; template <int EPI, int MI>
; DI void gemm_tile(const GemmDesc& g, int tm, int tn, char* smem) {
;     ...
;   const int rowA = wm * (32 * MI) + r, rowB = wn * 64 + r;
;   const int hk = hh ^ ((r & 7) ^ ((r >> 3) & 3));
;     ...
;   G_GLDS(0, 0);
;   asm volatile("s_waitcnt vmcnt(0)" ::: "memory");
;   __syncthreads();
;   for (int kt = 0; kt < nk; kt += 2) {
;     if (kt + 1 < nk) G_GLDS(kt + 1, 1);
;     G_COMPUTE(0);
;     asm volatile("s_waitcnt vmcnt(0)" ::: "memory");
;     __syncthreads();
;     if (kt + 1 < nk) {
;       if (kt + 2 < nk) G_GLDS(kt + 2, 0);
;       G_COMPUTE(1);
;       asm volatile("s_waitcnt vmcnt(0)" ::: "memory");
;       __syncthreads();
;     }
;   }
.Lgb_loop:
	ds_read_b128 v[232:235], v162 offset:8192
	s_waitcnt lgkmcnt(2)
	v_mfma_f32_32x32x16_bf16 v[80:95], v[224:227], v[236:239], v[80:95]
	v_mfma_f32_32x32x16_bf16 v[64:79], v[224:227], v[240:243], v[64:79]
	s_add_u32 m0, s100, 0x6000
	v_lshl_add_u64 v[106:107], v[252:253], 0, s[96:97]
	global_load_lds_dwordx4 v[106:107], off
	s_add_u32 m0, s100, 0x7000
	v_lshl_add_u64 v[106:107], v[252:253], 0, s[50:51]
	global_load_lds_dwordx4 v[106:107], off
	s_add_u32 m0, s100, 0x8000
	v_lshl_add_u64 v[106:107], v[252:253], 0, s[24:25]
	global_load_lds_dwordx4 v[106:107], off
	ds_read_b128 v[244:247], v167 offset:49152
	ds_read_b128 v[248:251], v167 offset:53248
	ds_read_b128 v[224:227], v163
	s_waitcnt lgkmcnt(4)
	v_mfma_f32_32x32x16_bf16 v[48:63], v[228:231], v[236:239], v[48:63]
	v_mfma_f32_32x32x16_bf16 v[32:47], v[228:231], v[240:243], v[32:47]
	s_add_u32 m0, s100, 0x9000
	v_lshl_add_u64 v[106:107], v[252:253], 0, s[26:27]
	global_load_lds_dwordx4 v[106:107], off
	s_add_u32 m0, s100, 0xa000
	v_lshl_add_u64 v[106:107], v[252:253], 0, s[28:29]
	global_load_lds_dwordx4 v[106:107], off
	s_add_u32 m0, s100, 0xb000
	v_lshl_add_u64 v[106:107], v[252:253], 0, s[30:31]
	global_load_lds_dwordx4 v[106:107], off
	v_lshl_add_u64 v[252:253], v[252:253], 0, s[0:1]
	ds_read_b128 v[228:231], v163 offset:4096
	s_waitcnt lgkmcnt(4)
	v_mfma_f32_32x32x16_bf16 v[16:31], v[232:235], v[236:239], v[16:31]
	v_mfma_f32_32x32x16_bf16 v[0:15], v[232:235], v[240:243], v[0:15]
	s_mov_b64 s[16:17], 0xb00080
	s_add_u32 m0, s100, 0x10000
	v_lshl_add_u64 v[106:107], v[254:255], 0, s[16:17]
	global_load_lds_dwordx4 v[106:107], off
	s_mov_b64 s[16:17], 0xb10080
	s_add_u32 m0, s100, 0x11000
	v_lshl_add_u64 v[106:107], v[254:255], 0, s[16:17]
	global_load_lds_dwordx4 v[106:107], off
	s_mov_b64 s[16:17], 0xb20080
	s_add_u32 m0, s100, 0x12000
	v_lshl_add_u64 v[106:107], v[254:255], 0, s[16:17]
	global_load_lds_dwordx4 v[106:107], off
	ds_read_b128 v[232:235], v163 offset:8192
	s_waitcnt lgkmcnt(2)
	v_mfma_f32_32x32x16_bf16 v[80:95], v[224:227], v[244:247], v[80:95]
	v_mfma_f32_32x32x16_bf16 v[64:79], v[224:227], v[248:251], v[64:79]
	s_mov_b64 s[16:17], 0xb30080
	s_add_u32 m0, s100, 0x13000
	v_lshl_add_u64 v[106:107], v[254:255], 0, s[16:17]
	global_load_lds_dwordx4 v[106:107], off
	v_lshl_add_u64 v[254:255], v[254:255], 0, s[0:1]
	ds_read_b128 v[236:239], v168 offset:49152
	ds_read_b128 v[240:243], v168 offset:53248
	ds_read_b128 v[224:227], v164
	s_waitcnt lgkmcnt(4)
	v_mfma_f32_32x32x16_bf16 v[48:63], v[228:231], v[244:247], v[48:63]
	v_mfma_f32_32x32x16_bf16 v[32:47], v[228:231], v[248:251], v[32:47]
	ds_read_b128 v[228:231], v164 offset:4096
	s_waitcnt lgkmcnt(4)
	v_mfma_f32_32x32x16_bf16 v[16:31], v[232:235], v[244:247], v[16:31]
	v_mfma_f32_32x32x16_bf16 v[0:15], v[232:235], v[248:251], v[0:15]
	ds_read_b128 v[232:235], v164 offset:8192
	s_waitcnt lgkmcnt(2)
	v_mfma_f32_32x32x16_bf16 v[80:95], v[224:227], v[236:239], v[80:95]
	v_mfma_f32_32x32x16_bf16 v[64:79], v[224:227], v[240:243], v[64:79]
	ds_read_b128 v[244:247], v169 offset:49152
	ds_read_b128 v[248:251], v169 offset:53248
	ds_read_b128 v[224:227], v165
	s_waitcnt lgkmcnt(4)
	v_mfma_f32_32x32x16_bf16 v[48:63], v[228:231], v[236:239], v[48:63]
	v_mfma_f32_32x32x16_bf16 v[32:47], v[228:231], v[240:243], v[32:47]
	ds_read_b128 v[228:231], v165 offset:4096
	s_waitcnt lgkmcnt(4)
	v_mfma_f32_32x32x16_bf16 v[16:31], v[232:235], v[236:239], v[16:31]
	v_mfma_f32_32x32x16_bf16 v[0:15], v[232:235], v[240:243], v[0:15]
	ds_read_b128 v[232:235], v165 offset:8192
	s_waitcnt lgkmcnt(2)
	v_mfma_f32_32x32x16_bf16 v[80:95], v[224:227], v[244:247], v[80:95]
	v_mfma_f32_32x32x16_bf16 v[64:79], v[224:227], v[248:251], v[64:79]
	s_waitcnt lgkmcnt(0)
	s_waitcnt vmcnt(0)
	s_barrier
	ds_read_b128 v[236:239], v170
	ds_read_b128 v[240:243], v170 offset:4096
	ds_read_b128 v[224:227], v162 offset:24576
	v_mfma_f32_32x32x16_bf16 v[48:63], v[228:231], v[244:247], v[48:63]
	v_mfma_f32_32x32x16_bf16 v[32:47], v[228:231], v[248:251], v[32:47]
	ds_read_b128 v[228:231], v162 offset:28672
	v_mfma_f32_32x32x16_bf16 v[16:31], v[232:235], v[244:247], v[16:31]
	v_mfma_f32_32x32x16_bf16 v[0:15], v[232:235], v[248:251], v[0:15]
	s_cmp_eq_u32 s101, 14
	s_cbranch_scc1 .Lgb_last
; template <int EPI, int MI>
; DI void gemm_tile(const GemmDesc& g, int tm, int tn, char* smem) {
;     ...
;   const int rowA = wm * (32 * MI) + r, rowB = wn * 64 + r;
;   const int hk = hh ^ ((r & 7) ^ ((r >> 3) & 3));
;     ...
;   G_GLDS(0, 0);
;   asm volatile("s_waitcnt vmcnt(0)" ::: "memory");
;   __syncthreads();
;   for (int kt = 0; kt < nk; kt += 2) {
;     if (kt + 1 < nk) G_GLDS(kt + 1, 1);
;     G_COMPUTE(0);
;     asm volatile("s_waitcnt vmcnt(0)" ::: "memory");
;     __syncthreads();
;     if (kt + 1 < nk) {
;       if (kt + 2 < nk) G_GLDS(kt + 2, 0);
;       G_COMPUTE(1);
;       asm volatile("s_waitcnt vmcnt(0)" ::: "memory");
;       __syncthreads();
;     }
;   }
	ds_read_b128 v[232:235], v162 offset:32768
	s_waitcnt lgkmcnt(2)
	v_mfma_f32_32x32x16_bf16 v[80:95], v[224:227], v[236:239], v[80:95]
	v_mfma_f32_32x32x16_bf16 v[64:79], v[224:227], v[240:243], v[64:79]
	s_mov_b32 m0, s100
	v_lshl_add_u64 v[106:107], v[252:253], 0, s[96:97]
	global_load_lds_dwordx4 v[106:107], off
	s_add_u32 m0, s100, 0x1000
	v_lshl_add_u64 v[106:107], v[252:253], 0, s[50:51]
	global_load_lds_dwordx4 v[106:107], off
	s_add_u32 m0, s100, 0x2000
	v_lshl_add_u64 v[106:107], v[252:253], 0, s[24:25]
	global_load_lds_dwordx4 v[106:107], off
	ds_read_b128 v[244:247], v171
	ds_read_b128 v[248:251], v171 offset:4096
	ds_read_b128 v[224:227], v163 offset:24576
	s_waitcnt lgkmcnt(4)
	v_mfma_f32_32x32x16_bf16 v[48:63], v[228:231], v[236:239], v[48:63]
	v_mfma_f32_32x32x16_bf16 v[32:47], v[228:231], v[240:243], v[32:47]
	s_add_u32 m0, s100, 0x3000
	v_lshl_add_u64 v[106:107], v[252:253], 0, s[26:27]
	global_load_lds_dwordx4 v[106:107], off
	s_add_u32 m0, s100, 0x4000
	v_lshl_add_u64 v[106:107], v[252:253], 0, s[28:29]
	global_load_lds_dwordx4 v[106:107], off
	s_add_u32 m0, s100, 0x5000
	v_lshl_add_u64 v[106:107], v[252:253], 0, s[30:31]
	global_load_lds_dwordx4 v[106:107], off
	v_lshl_add_u64 v[252:253], v[252:253], 0, s[0:1]
	ds_read_b128 v[228:231], v163 offset:28672
	s_waitcnt lgkmcnt(4)
	v_mfma_f32_32x32x16_bf16 v[16:31], v[232:235], v[236:239], v[16:31]
	v_mfma_f32_32x32x16_bf16 v[0:15], v[232:235], v[240:243], v[0:15]
	s_mov_b64 s[16:17], 0xb00080
	s_add_u32 m0, s100, 0xc000
	v_lshl_add_u64 v[106:107], v[254:255], 0, s[16:17]
	global_load_lds_dwordx4 v[106:107], off
	s_mov_b64 s[16:17], 0xb10080
	s_add_u32 m0, s100, 0xd000
	v_lshl_add_u64 v[106:107], v[254:255], 0, s[16:17]
	global_load_lds_dwordx4 v[106:107], off
	s_mov_b64 s[16:17], 0xb20080
	s_add_u32 m0, s100, 0xe000
	v_lshl_add_u64 v[106:107], v[254:255], 0, s[16:17]
	global_load_lds_dwordx4 v[106:107], off
	ds_read_b128 v[232:235], v163 offset:32768
	s_waitcnt lgkmcnt(2)
	v_mfma_f32_32x32x16_bf16 v[80:95], v[224:227], v[244:247], v[80:95]
	v_mfma_f32_32x32x16_bf16 v[64:79], v[224:227], v[248:251], v[64:79]
	s_mov_b64 s[16:17], 0xb30080
	s_add_u32 m0, s100, 0xf000
	v_lshl_add_u64 v[106:107], v[254:255], 0, s[16:17]
	global_load_lds_dwordx4 v[106:107], off
	v_lshl_add_u64 v[254:255], v[254:255], 0, s[0:1]
	ds_read_b128 v[236:239], v172
	ds_read_b128 v[240:243], v172 offset:4096
	ds_read_b128 v[224:227], v164 offset:24576
	s_waitcnt lgkmcnt(4)
	v_mfma_f32_32x32x16_bf16 v[48:63], v[228:231], v[244:247], v[48:63]
	v_mfma_f32_32x32x16_bf16 v[32:47], v[228:231], v[248:251], v[32:47]
	ds_read_b128 v[228:231], v164 offset:28672
	s_waitcnt lgkmcnt(4)
	v_mfma_f32_32x32x16_bf16 v[16:31], v[232:235], v[244:247], v[16:31]
	v_mfma_f32_32x32x16_bf16 v[0:15], v[232:235], v[248:251], v[0:15]
	ds_read_b128 v[232:235], v164 offset:32768
	s_waitcnt lgkmcnt(2)
	v_mfma_f32_32x32x16_bf16 v[80:95], v[224:227], v[236:239], v[80:95]
	v_mfma_f32_32x32x16_bf16 v[64:79], v[224:227], v[240:243], v[64:79]
	ds_read_b128 v[244:247], v173
	ds_read_b128 v[248:251], v173 offset:4096
	ds_read_b128 v[224:227], v165 offset:24576
	s_waitcnt lgkmcnt(4)
	v_mfma_f32_32x32x16_bf16 v[48:63], v[228:231], v[236:239], v[48:63]
	v_mfma_f32_32x32x16_bf16 v[32:47], v[228:231], v[240:243], v[32:47]
	ds_read_b128 v[228:231], v165 offset:28672
	s_waitcnt lgkmcnt(4)
	v_mfma_f32_32x32x16_bf16 v[16:31], v[232:235], v[236:239], v[16:31]
	v_mfma_f32_32x32x16_bf16 v[0:15], v[232:235], v[240:243], v[0:15]
	ds_read_b128 v[232:235], v165 offset:32768
	s_waitcnt lgkmcnt(2)
	v_mfma_f32_32x32x16_bf16 v[80:95], v[224:227], v[244:247], v[80:95]
	v_mfma_f32_32x32x16_bf16 v[64:79], v[224:227], v[248:251], v[64:79]
	s_waitcnt lgkmcnt(0)
	s_waitcnt vmcnt(0)
	s_barrier
	ds_read_b128 v[236:239], v166 offset:49152
	ds_read_b128 v[240:243], v166 offset:53248
	ds_read_b128 v[224:227], v162
	v_mfma_f32_32x32x16_bf16 v[48:63], v[228:231], v[244:247], v[48:63]
	v_mfma_f32_32x32x16_bf16 v[32:47], v[228:231], v[248:251], v[32:47]
	ds_read_b128 v[228:231], v162 offset:4096
	v_mfma_f32_32x32x16_bf16 v[16:31], v[232:235], v[244:247], v[16:31]
	v_mfma_f32_32x32x16_bf16 v[0:15], v[232:235], v[248:251], v[0:15]
	s_add_u32 s101, s101, 2
	s_branch .Lgb_loop

; template <int EPI, int MI>
; DI void gemm_tile(const GemmDesc& g, int tm, int tn, char* smem) {
;     ...
;   const int rowA = wm * (32 * MI) + r, rowB = wn * 64 + r;
;   const int hk = hh ^ ((r & 7) ^ ((r >> 3) & 3));
;     ...
;   G_GLDS(0, 0);
;   asm volatile("s_waitcnt vmcnt(0)" ::: "memory");
;   __syncthreads();
;   for (int kt = 0; kt < nk; kt += 2) {
;     if (kt + 1 < nk) G_GLDS(kt + 1, 1);
;     G_COMPUTE(0);
;     asm volatile("s_waitcnt vmcnt(0)" ::: "memory");
;     __syncthreads();
;     if (kt + 1 < nk) {
;       if (kt + 2 < nk) G_GLDS(kt + 2, 0);
;       G_COMPUTE(1);
;       asm volatile("s_waitcnt vmcnt(0)" ::: "memory");
;       __syncthreads();
;     }
;   }
.Lgf_loop:
	ds_read_b128 v[248:251], v98 offset:32768
	ds_read_b128 v[252:255], v98 offset:36864
	ds_read_b128 v[232:235], v93
	s_waitcnt lgkmcnt(4)
	v_mfma_f32_32x32x16_bf16 v[48:63], v[224:227], v[240:243], v[48:63]
	v_mfma_f32_32x32x16_bf16 v[32:47], v[224:227], v[244:247], v[32:47]
	s_mov_b64 s[4:5], 0x5872080
	s_add_u32 m0, s100, 0x4000
	v_lshl_add_u64 v[102:103], v[104:105], 0, s[4:5]
	global_load_lds_dwordx4 v[102:103], off
	s_mov_b64 s[4:5], 0x589e080
	s_add_u32 m0, s100, 0x5000
	v_lshl_add_u64 v[102:103], v[104:105], 0, s[4:5]
	global_load_lds_dwordx4 v[102:103], off
	s_mov_b64 s[4:5], 0x58ca080
	s_add_u32 m0, s100, 0x6000
	v_lshl_add_u64 v[102:103], v[104:105], 0, s[4:5]
	global_load_lds_dwordx4 v[102:103], off
	ds_read_b128 v[236:239], v93 offset:4096
	s_waitcnt lgkmcnt(4)
	v_mfma_f32_32x32x16_bf16 v[16:31], v[228:231], v[240:243], v[16:31]
	v_mfma_f32_32x32x16_bf16 v[0:15], v[228:231], v[244:247], v[0:15]
	s_mov_b64 s[4:5], 0x58f6080
	s_add_u32 m0, s100, 0x7000
	v_lshl_add_u64 v[102:103], v[104:105], 0, s[4:5]
	global_load_lds_dwordx4 v[102:103], off
	v_lshl_add_u64 v[104:105], v[104:105], 0, s[46:47]
	s_mov_b64 s[4:5], 0x1b80080
	s_add_u32 m0, s100, 0xc000
	v_lshl_add_u64 v[102:103], v[106:107], 0, s[4:5]
	global_load_lds_dwordx4 v[102:103], off
	s_mov_b64 s[4:5], 0x1bac080
	s_add_u32 m0, s100, 0xd000
	v_lshl_add_u64 v[102:103], v[106:107], 0, s[4:5]
	global_load_lds_dwordx4 v[102:103], off
	ds_read_b128 v[240:243], v99 offset:32768
	ds_read_b128 v[244:247], v99 offset:36864
	ds_read_b128 v[224:227], v94
	s_waitcnt lgkmcnt(4)
	v_mfma_f32_32x32x16_bf16 v[48:63], v[232:235], v[248:251], v[48:63]
	v_mfma_f32_32x32x16_bf16 v[32:47], v[232:235], v[252:255], v[32:47]
	s_mov_b64 s[4:5], 0x1bd8080
	s_add_u32 m0, s100, 0xe000
	v_lshl_add_u64 v[102:103], v[106:107], 0, s[4:5]
	global_load_lds_dwordx4 v[102:103], off
	s_mov_b64 s[4:5], 0x1c04080
	s_add_u32 m0, s100, 0xf000
	v_lshl_add_u64 v[102:103], v[106:107], 0, s[4:5]
	global_load_lds_dwordx4 v[102:103], off
	v_lshl_add_u64 v[106:107], v[106:107], 0, s[46:47]
	ds_read_b128 v[228:231], v94 offset:4096
	s_waitcnt lgkmcnt(4)
	v_mfma_f32_32x32x16_bf16 v[16:31], v[236:239], v[248:251], v[16:31]
	v_mfma_f32_32x32x16_bf16 v[0:15], v[236:239], v[252:255], v[0:15]
	ds_read_b128 v[248:251], v100 offset:32768
	ds_read_b128 v[252:255], v100 offset:36864
	ds_read_b128 v[232:235], v95
	s_waitcnt lgkmcnt(4)
	v_mfma_f32_32x32x16_bf16 v[48:63], v[224:227], v[240:243], v[48:63]
	v_mfma_f32_32x32x16_bf16 v[32:47], v[224:227], v[244:247], v[32:47]
	ds_read_b128 v[236:239], v95 offset:4096
	s_waitcnt lgkmcnt(4)
	v_mfma_f32_32x32x16_bf16 v[16:31], v[228:231], v[240:243], v[16:31]
	v_mfma_f32_32x32x16_bf16 v[0:15], v[228:231], v[244:247], v[0:15]
	s_waitcnt lgkmcnt(0)
	s_waitcnt vmcnt(0)
	s_barrier
	ds_read_b128 v[240:243], v97 offset:49152
	ds_read_b128 v[244:247], v97 offset:53248
	ds_read_b128 v[224:227], v92 offset:16384
	v_mfma_f32_32x32x16_bf16 v[48:63], v[232:235], v[248:251], v[48:63]
	v_mfma_f32_32x32x16_bf16 v[32:47], v[232:235], v[252:255], v[32:47]
	ds_read_b128 v[228:231], v92 offset:20480
	v_mfma_f32_32x32x16_bf16 v[16:31], v[236:239], v[248:251], v[16:31]
	v_mfma_f32_32x32x16_bf16 v[0:15], v[236:239], v[252:255], v[0:15]
	s_cmp_eq_u32 s101, 42
	s_cbranch_scc1 .Lgf_last
	ds_read_b128 v[248:251], v98 offset:49152
	ds_read_b128 v[252:255], v98 offset:53248
	ds_read_b128 v[232:235], v93 offset:16384
	s_waitcnt lgkmcnt(4)
	v_mfma_f32_32x32x16_bf16 v[48:63], v[224:227], v[240:243], v[48:63]
	v_mfma_f32_32x32x16_bf16 v[32:47], v[224:227], v[244:247], v[32:47]
	s_mov_b64 s[4:5], 0x5872080
	s_mov_b32 m0, s100
	v_lshl_add_u64 v[102:103], v[104:105], 0, s[4:5]
	global_load_lds_dwordx4 v[102:103], off
	s_mov_b64 s[4:5], 0x589e080
	s_add_u32 m0, s100, 0x1000
	v_lshl_add_u64 v[102:103], v[104:105], 0, s[4:5]
	global_load_lds_dwordx4 v[102:103], off
	s_mov_b64 s[4:5], 0x58ca080
	s_add_u32 m0, s100, 0x2000
	v_lshl_add_u64 v[102:103], v[104:105], 0, s[4:5]
	global_load_lds_dwordx4 v[102:103], off
	ds_read_b128 v[236:239], v93 offset:20480
	s_waitcnt lgkmcnt(4)
	v_mfma_f32_32x32x16_bf16 v[16:31], v[228:231], v[240:243], v[16:31]
	v_mfma_f32_32x32x16_bf16 v[0:15], v[228:231], v[244:247], v[0:15]
	s_mov_b64 s[4:5], 0x58f6080
	s_add_u32 m0, s100, 0x3000
	v_lshl_add_u64 v[102:103], v[104:105], 0, s[4:5]
	global_load_lds_dwordx4 v[102:103], off
	v_lshl_add_u64 v[104:105], v[104:105], 0, s[46:47]
	s_mov_b64 s[4:5], 0x1b80080
	s_add_u32 m0, s100, 0x8000
	v_lshl_add_u64 v[102:103], v[106:107], 0, s[4:5]
	global_load_lds_dwordx4 v[102:103], off
	s_mov_b64 s[4:5], 0x1bac080
	s_add_u32 m0, s100, 0x9000
	v_lshl_add_u64 v[102:103], v[106:107], 0, s[4:5]
	global_load_lds_dwordx4 v[102:103], off
	ds_read_b128 v[240:243], v99 offset:49152
	ds_read_b128 v[244:247], v99 offset:53248
	ds_read_b128 v[224:227], v94 offset:16384
	s_waitcnt lgkmcnt(4)
	v_mfma_f32_32x32x16_bf16 v[48:63], v[232:235], v[248:251], v[48:63]
	v_mfma_f32_32x32x16_bf16 v[32:47], v[232:235], v[252:255], v[32:47]
	s_mov_b64 s[4:5], 0x1bd8080
	s_add_u32 m0, s100, 0xa000
	v_lshl_add_u64 v[102:103], v[106:107], 0, s[4:5]
	global_load_lds_dwordx4 v[102:103], off
	s_mov_b64 s[4:5], 0x1c04080
	s_add_u32 m0, s100, 0xb000
	v_lshl_add_u64 v[102:103], v[106:107], 0, s[4:5]
	global_load_lds_dwordx4 v[102:103], off
	v_lshl_add_u64 v[106:107], v[106:107], 0, s[46:47]
	ds_read_b128 v[228:231], v94 offset:20480
	s_waitcnt lgkmcnt(4)
	v_mfma_f32_32x32x16_bf16 v[16:31], v[236:239], v[248:251], v[16:31]
	v_mfma_f32_32x32x16_bf16 v[0:15], v[236:239], v[252:255], v[0:15]
	ds_read_b128 v[248:251], v100 offset:49152
	ds_read_b128 v[252:255], v100 offset:53248
	ds_read_b128 v[232:235], v95 offset:16384
	s_waitcnt lgkmcnt(4)
	v_mfma_f32_32x32x16_bf16 v[48:63], v[224:227], v[240:243], v[48:63]
	v_mfma_f32_32x32x16_bf16 v[32:47], v[224:227], v[244:247], v[32:47]
	ds_read_b128 v[236:239], v95 offset:20480
	s_waitcnt lgkmcnt(4)
	v_mfma_f32_32x32x16_bf16 v[16:31], v[228:231], v[240:243], v[16:31]
	v_mfma_f32_32x32x16_bf16 v[0:15], v[228:231], v[244:247], v[0:15]
	s_waitcnt lgkmcnt(0)
	s_waitcnt vmcnt(0)
	s_barrier
	ds_read_b128 v[240:243], v97 offset:32768
	ds_read_b128 v[244:247], v97 offset:36864
	ds_read_b128 v[224:227], v92
	v_mfma_f32_32x32x16_bf16 v[48:63], v[232:235], v[248:251], v[48:63]
	v_mfma_f32_32x32x16_bf16 v[32:47], v[232:235], v[252:255], v[32:47]
	ds_read_b128 v[228:231], v92 offset:4096
	v_mfma_f32_32x32x16_bf16 v[16:31], v[236:239], v[248:251], v[16:31]
	v_mfma_f32_32x32x16_bf16 v[0:15], v[236:239], v[252:255], v[0:15]
	s_add_u32 s101, s101, 2
	s_branch .Lgf_loop

; template <int EPI, int MI>
; DI void gemm_tile(const GemmDesc& g, int tm, int tn, char* smem) {
;     ...
;   const int rowA = wm * (32 * MI) + r, rowB = wn * 64 + r;
;   const int hk = hh ^ ((r & 7) ^ ((r >> 3) & 3));
;     ...
;   G_GLDS(0, 0);
;   asm volatile("s_waitcnt vmcnt(0)" ::: "memory");
;   __syncthreads();
;   for (int kt = 0; kt < nk; kt += 2) {
;     if (kt + 1 < nk) G_GLDS(kt + 1, 1);
;     G_COMPUTE(0);
;     asm volatile("s_waitcnt vmcnt(0)" ::: "memory");
;     __syncthreads();
;     if (kt + 1 < nk) {
;       if (kt + 2 < nk) G_GLDS(kt + 2, 0);
;       G_COMPUTE(1);
;       asm volatile("s_waitcnt vmcnt(0)" ::: "memory");
;       __syncthreads();
;     }
;   }
.Lge_loop:
	ds_read_b128 v[232:235], v162 offset:8192
	s_waitcnt lgkmcnt(2)
	v_mfma_f32_32x32x16_bf16 v[80:95], v[224:227], v[236:239], v[80:95]
	v_mfma_f32_32x32x16_bf16 v[64:79], v[224:227], v[240:243], v[64:79]
	s_mov_b64 s[16:17], 0x5872080
	s_add_u32 m0, s100, 0x6000
	v_lshl_add_u64 v[106:107], v[252:253], 0, s[16:17]
	global_load_lds_dwordx4 v[106:107], off
	s_mov_b64 s[16:17], 0x589e080
	s_add_u32 m0, s100, 0x7000
	v_lshl_add_u64 v[106:107], v[252:253], 0, s[16:17]
	global_load_lds_dwordx4 v[106:107], off
	s_mov_b64 s[16:17], 0x58ca080
	s_add_u32 m0, s100, 0x8000
	v_lshl_add_u64 v[106:107], v[252:253], 0, s[16:17]
	global_load_lds_dwordx4 v[106:107], off
	ds_read_b128 v[244:247], v167 offset:49152
	ds_read_b128 v[248:251], v167 offset:53248
	ds_read_b128 v[224:227], v163
	s_waitcnt lgkmcnt(4)
	v_mfma_f32_32x32x16_bf16 v[48:63], v[228:231], v[236:239], v[48:63]
	v_mfma_f32_32x32x16_bf16 v[32:47], v[228:231], v[240:243], v[32:47]
	s_mov_b64 s[16:17], 0x58f6080
	s_add_u32 m0, s100, 0x9000
	v_lshl_add_u64 v[106:107], v[252:253], 0, s[16:17]
	global_load_lds_dwordx4 v[106:107], off
	s_mov_b64 s[16:17], 0x5922080
	s_add_u32 m0, s100, 0xa000
	v_lshl_add_u64 v[106:107], v[252:253], 0, s[16:17]
	global_load_lds_dwordx4 v[106:107], off
	s_mov_b64 s[16:17], 0x594e080
	s_add_u32 m0, s100, 0xb000
	v_lshl_add_u64 v[106:107], v[252:253], 0, s[16:17]
	global_load_lds_dwordx4 v[106:107], off
	v_lshl_add_u64 v[252:253], v[252:253], 0, s[4:5]
	ds_read_b128 v[228:231], v163 offset:4096
	s_waitcnt lgkmcnt(4)
	v_mfma_f32_32x32x16_bf16 v[16:31], v[232:235], v[236:239], v[16:31]
	v_mfma_f32_32x32x16_bf16 v[0:15], v[232:235], v[240:243], v[0:15]
	s_mov_b64 s[16:17], 0x1b80080
	s_add_u32 m0, s100, 0x10000
	v_lshl_add_u64 v[106:107], v[254:255], 0, s[16:17]
	global_load_lds_dwordx4 v[106:107], off
	s_mov_b64 s[16:17], 0x1bac080
	s_add_u32 m0, s100, 0x11000
	v_lshl_add_u64 v[106:107], v[254:255], 0, s[16:17]
	global_load_lds_dwordx4 v[106:107], off
	s_mov_b64 s[16:17], 0x1bd8080
	s_add_u32 m0, s100, 0x12000
	v_lshl_add_u64 v[106:107], v[254:255], 0, s[16:17]
	global_load_lds_dwordx4 v[106:107], off
	ds_read_b128 v[232:235], v163 offset:8192
	s_waitcnt lgkmcnt(2)
	v_mfma_f32_32x32x16_bf16 v[80:95], v[224:227], v[244:247], v[80:95]
	v_mfma_f32_32x32x16_bf16 v[64:79], v[224:227], v[248:251], v[64:79]
	s_mov_b64 s[16:17], 0x1c04080
	s_add_u32 m0, s100, 0x13000
	v_lshl_add_u64 v[106:107], v[254:255], 0, s[16:17]
	global_load_lds_dwordx4 v[106:107], off
	v_lshl_add_u64 v[254:255], v[254:255], 0, s[4:5]
	ds_read_b128 v[236:239], v168 offset:49152
	ds_read_b128 v[240:243], v168 offset:53248
	ds_read_b128 v[224:227], v164
	s_waitcnt lgkmcnt(4)
	v_mfma_f32_32x32x16_bf16 v[48:63], v[228:231], v[244:247], v[48:63]
	v_mfma_f32_32x32x16_bf16 v[32:47], v[228:231], v[248:251], v[32:47]
	ds_read_b128 v[228:231], v164 offset:4096
	s_waitcnt lgkmcnt(4)
	v_mfma_f32_32x32x16_bf16 v[16:31], v[232:235], v[244:247], v[16:31]
	v_mfma_f32_32x32x16_bf16 v[0:15], v[232:235], v[248:251], v[0:15]
	ds_read_b128 v[232:235], v164 offset:8192
	s_waitcnt lgkmcnt(2)
	v_mfma_f32_32x32x16_bf16 v[80:95], v[224:227], v[236:239], v[80:95]
	v_mfma_f32_32x32x16_bf16 v[64:79], v[224:227], v[240:243], v[64:79]
	ds_read_b128 v[244:247], v169 offset:49152
	ds_read_b128 v[248:251], v169 offset:53248
	ds_read_b128 v[224:227], v165
	s_waitcnt lgkmcnt(4)
	v_mfma_f32_32x32x16_bf16 v[48:63], v[228:231], v[236:239], v[48:63]
	v_mfma_f32_32x32x16_bf16 v[32:47], v[228:231], v[240:243], v[32:47]
	ds_read_b128 v[228:231], v165 offset:4096
	s_waitcnt lgkmcnt(4)
	v_mfma_f32_32x32x16_bf16 v[16:31], v[232:235], v[236:239], v[16:31]
	v_mfma_f32_32x32x16_bf16 v[0:15], v[232:235], v[240:243], v[0:15]
	ds_read_b128 v[232:235], v165 offset:8192
	s_waitcnt lgkmcnt(2)
	v_mfma_f32_32x32x16_bf16 v[80:95], v[224:227], v[244:247], v[80:95]
	v_mfma_f32_32x32x16_bf16 v[64:79], v[224:227], v[248:251], v[64:79]
	s_waitcnt lgkmcnt(0)
	s_waitcnt vmcnt(0)
	s_barrier
	ds_read_b128 v[236:239], v170
	ds_read_b128 v[240:243], v170 offset:4096
	ds_read_b128 v[224:227], v162 offset:24576
	v_mfma_f32_32x32x16_bf16 v[48:63], v[228:231], v[244:247], v[48:63]
	v_mfma_f32_32x32x16_bf16 v[32:47], v[228:231], v[248:251], v[32:47]
	ds_read_b128 v[228:231], v162 offset:28672
	v_mfma_f32_32x32x16_bf16 v[16:31], v[232:235], v[244:247], v[16:31]
	v_mfma_f32_32x32x16_bf16 v[0:15], v[232:235], v[248:251], v[0:15]
	s_cmp_eq_u32 s15, 42
	s_cbranch_scc1 .Lge_last
; template <int EPI, int MI>
; DI void gemm_tile(const GemmDesc& g, int tm, int tn, char* smem) {
;     ...
;   const int rowA = wm * (32 * MI) + r, rowB = wn * 64 + r;
;   const int hk = hh ^ ((r & 7) ^ ((r >> 3) & 3));
;     ...
;   G_GLDS(0, 0);
;   asm volatile("s_waitcnt vmcnt(0)" ::: "memory");
;   __syncthreads();
;   for (int kt = 0; kt < nk; kt += 2) {
;     if (kt + 1 < nk) G_GLDS(kt + 1, 1);
;     G_COMPUTE(0);
;     asm volatile("s_waitcnt vmcnt(0)" ::: "memory");
;     __syncthreads();
;     if (kt + 1 < nk) {
;       if (kt + 2 < nk) G_GLDS(kt + 2, 0);
;       G_COMPUTE(1);
;       asm volatile("s_waitcnt vmcnt(0)" ::: "memory");
;       __syncthreads();
;     }
;   }
	ds_read_b128 v[232:235], v162 offset:32768
	s_waitcnt lgkmcnt(2)
	v_mfma_f32_32x32x16_bf16 v[80:95], v[224:227], v[236:239], v[80:95]
	v_mfma_f32_32x32x16_bf16 v[64:79], v[224:227], v[240:243], v[64:79]
	s_mov_b64 s[16:17], 0x5872080
	s_mov_b32 m0, s100
	v_lshl_add_u64 v[106:107], v[252:253], 0, s[16:17]
	global_load_lds_dwordx4 v[106:107], off
	s_mov_b64 s[16:17], 0x589e080
	s_add_u32 m0, s100, 0x1000
	v_lshl_add_u64 v[106:107], v[252:253], 0, s[16:17]
	global_load_lds_dwordx4 v[106:107], off
	s_mov_b64 s[16:17], 0x58ca080
	s_add_u32 m0, s100, 0x2000
	v_lshl_add_u64 v[106:107], v[252:253], 0, s[16:17]
	global_load_lds_dwordx4 v[106:107], off
	ds_read_b128 v[244:247], v171
	ds_read_b128 v[248:251], v171 offset:4096
	ds_read_b128 v[224:227], v163 offset:24576
	s_waitcnt lgkmcnt(4)
	v_mfma_f32_32x32x16_bf16 v[48:63], v[228:231], v[236:239], v[48:63]
	v_mfma_f32_32x32x16_bf16 v[32:47], v[228:231], v[240:243], v[32:47]
	s_mov_b64 s[16:17], 0x58f6080
	s_add_u32 m0, s100, 0x3000
	v_lshl_add_u64 v[106:107], v[252:253], 0, s[16:17]
	global_load_lds_dwordx4 v[106:107], off
	s_mov_b64 s[16:17], 0x5922080
	s_add_u32 m0, s100, 0x4000
	v_lshl_add_u64 v[106:107], v[252:253], 0, s[16:17]
	global_load_lds_dwordx4 v[106:107], off
	s_mov_b64 s[16:17], 0x594e080
	s_add_u32 m0, s100, 0x5000
	v_lshl_add_u64 v[106:107], v[252:253], 0, s[16:17]
	global_load_lds_dwordx4 v[106:107], off
	v_lshl_add_u64 v[252:253], v[252:253], 0, s[4:5]
	ds_read_b128 v[228:231], v163 offset:28672
	s_waitcnt lgkmcnt(4)
	v_mfma_f32_32x32x16_bf16 v[16:31], v[232:235], v[236:239], v[16:31]
	v_mfma_f32_32x32x16_bf16 v[0:15], v[232:235], v[240:243], v[0:15]
	s_mov_b64 s[16:17], 0x1b80080
	s_add_u32 m0, s100, 0xc000
	v_lshl_add_u64 v[106:107], v[254:255], 0, s[16:17]
	global_load_lds_dwordx4 v[106:107], off
	s_mov_b64 s[16:17], 0x1bac080
	s_add_u32 m0, s100, 0xd000
	v_lshl_add_u64 v[106:107], v[254:255], 0, s[16:17]
	global_load_lds_dwordx4 v[106:107], off
	s_mov_b64 s[16:17], 0x1bd8080
	s_add_u32 m0, s100, 0xe000
	v_lshl_add_u64 v[106:107], v[254:255], 0, s[16:17]
	global_load_lds_dwordx4 v[106:107], off
	ds_read_b128 v[232:235], v163 offset:32768
	s_waitcnt lgkmcnt(2)
	v_mfma_f32_32x32x16_bf16 v[80:95], v[224:227], v[244:247], v[80:95]
	v_mfma_f32_32x32x16_bf16 v[64:79], v[224:227], v[248:251], v[64:79]
	s_mov_b64 s[16:17], 0x1c04080
	s_add_u32 m0, s100, 0xf000
	v_lshl_add_u64 v[106:107], v[254:255], 0, s[16:17]
	global_load_lds_dwordx4 v[106:107], off
	v_lshl_add_u64 v[254:255], v[254:255], 0, s[4:5]
	ds_read_b128 v[236:239], v172
	ds_read_b128 v[240:243], v172 offset:4096
	ds_read_b128 v[224:227], v164 offset:24576
	s_waitcnt lgkmcnt(4)
	v_mfma_f32_32x32x16_bf16 v[48:63], v[228:231], v[244:247], v[48:63]
	v_mfma_f32_32x32x16_bf16 v[32:47], v[228:231], v[248:251], v[32:47]
	ds_read_b128 v[228:231], v164 offset:28672
	s_waitcnt lgkmcnt(4)
	v_mfma_f32_32x32x16_bf16 v[16:31], v[232:235], v[244:247], v[16:31]
	v_mfma_f32_32x32x16_bf16 v[0:15], v[232:235], v[248:251], v[0:15]
	ds_read_b128 v[232:235], v164 offset:32768
	s_waitcnt lgkmcnt(2)
	v_mfma_f32_32x32x16_bf16 v[80:95], v[224:227], v[236:239], v[80:95]
	v_mfma_f32_32x32x16_bf16 v[64:79], v[224:227], v[240:243], v[64:79]
	ds_read_b128 v[244:247], v173
	ds_read_b128 v[248:251], v173 offset:4096
	ds_read_b128 v[224:227], v165 offset:24576
	s_waitcnt lgkmcnt(4)
	v_mfma_f32_32x32x16_bf16 v[48:63], v[228:231], v[236:239], v[48:63]
	v_mfma_f32_32x32x16_bf16 v[32:47], v[228:231], v[240:243], v[32:47]
	ds_read_b128 v[228:231], v165 offset:28672
	s_waitcnt lgkmcnt(4)
	v_mfma_f32_32x32x16_bf16 v[16:31], v[232:235], v[236:239], v[16:31]
	v_mfma_f32_32x32x16_bf16 v[0:15], v[232:235], v[240:243], v[0:15]
	ds_read_b128 v[232:235], v165 offset:32768
	s_waitcnt lgkmcnt(2)
	v_mfma_f32_32x32x16_bf16 v[80:95], v[224:227], v[244:247], v[80:95]
	v_mfma_f32_32x32x16_bf16 v[64:79], v[224:227], v[248:251], v[64:79]
	s_waitcnt lgkmcnt(0)
	s_waitcnt vmcnt(0)
	s_barrier
	ds_read_b128 v[236:239], v166 offset:49152
	ds_read_b128 v[240:243], v166 offset:53248
	ds_read_b128 v[224:227], v162
	v_mfma_f32_32x32x16_bf16 v[48:63], v[228:231], v[244:247], v[48:63]
	v_mfma_f32_32x32x16_bf16 v[32:47], v[228:231], v[248:251], v[32:47]
	ds_read_b128 v[228:231], v162 offset:4096
	v_mfma_f32_32x32x16_bf16 v[16:31], v[232:235], v[244:247], v[16:31]
	v_mfma_f32_32x32x16_bf16 v[0:15], v[232:235], v[248:251], v[0:15]
	s_add_u32 s15, s15, 2
	s_branch .Lge_loop
